# attention epilogue: last butterfly round via v_permlane16_swap on a copy instead of ds_bpermute
# baseline (speedup 1.0000x reference)
.LBB0_303:
	s_cmpk_gt_u32 s65, 0xff
	s_waitcnt lgkmcnt(0)
	s_barrier
	s_cbranch_scc1 .LBB0_275
	s_mulk_i32 s64, 0x2200
	s_add_i32 s34, s64, 0
	s_add_i32 s34, s34, 0x10000
	ds_read2st64_b32 v[130:131], v71 offset1:1
	ds_read2st64_b32 v[132:133], v71 offset0:2 offset1:3
	ds_read2st64_b32 v[134:135], v71 offset0:4 offset1:5
	ds_read2st64_b32 v[136:137], v71 offset0:6 offset1:7
	ds_read2st64_b32 v[138:139], v71 offset0:8 offset1:9
	ds_read2st64_b32 v[140:141], v71 offset0:10 offset1:11
	ds_read2st64_b32 v[142:143], v71 offset0:12 offset1:13
	ds_read2st64_b32 v[144:145], v71 offset0:14 offset1:15
	ds_read2st64_b32 v[146:147], v71 offset0:16 offset1:17
	ds_read2st64_b32 v[148:149], v71 offset0:18 offset1:19
	ds_read2st64_b32 v[150:151], v71 offset0:20 offset1:21
	ds_read2st64_b32 v[172:173], v71 offset0:22 offset1:23
	ds_read2st64_b32 v[174:175], v71 offset0:24 offset1:25
	ds_read2st64_b32 v[176:177], v71 offset0:26 offset1:27
	ds_read2st64_b32 v[178:179], v71 offset0:28 offset1:29
	ds_read2st64_b32 v[180:181], v71 offset0:30 offset1:31
	ds_read2st64_b32 v[182:183], v71 offset0:32 offset1:33
	ds_read2st64_b32 v[184:185], v71 offset0:34 offset1:35
	ds_read2st64_b32 v[186:187], v71 offset0:36 offset1:37
	ds_read2st64_b32 v[188:189], v71 offset0:38 offset1:39
	ds_read2st64_b32 v[190:191], v71 offset0:40 offset1:41
	ds_read2st64_b32 v[192:193], v71 offset0:42 offset1:43
	ds_read2st64_b32 v[194:195], v71 offset0:44 offset1:45
	ds_read2st64_b32 v[196:197], v71 offset0:46 offset1:47
	ds_read2st64_b32 v[198:199], v71 offset0:48 offset1:49
	ds_read2st64_b32 v[200:201], v71 offset0:50 offset1:51
	ds_read2st64_b32 v[202:203], v71 offset0:52 offset1:53
	ds_read2st64_b32 v[204:205], v71 offset0:54 offset1:55
	ds_read2st64_b32 v[206:207], v71 offset0:56 offset1:57
	ds_read2st64_b32 v[208:209], v71 offset0:58 offset1:59
	ds_read2st64_b32 v[210:211], v71 offset0:60 offset1:61
	ds_read2st64_b32 v[212:213], v71 offset0:62 offset1:63
	s_waitcnt lgkmcnt(15)
	v_sub_f32_e32 v60, v72, v130
	v_sub_f32_e32 v55, v0, v131
	v_sub_f32_e32 v52, v73, v132
	v_sub_f32_e32 v47, v74, v133
	v_sub_f32_e32 v44, v3, v134
	v_sub_f32_e32 v39, v36, v135
	v_sub_f32_e32 v28, v23, v138
	v_sub_f32_e32 v23, v38, v139
	v_sub_f32_e32 v36, v20, v136
	v_sub_f32_e32 v31, v6, v137
	v_sub_f32_e32 v20, v41, v140
	v_sub_f32_e32 v15, v26, v141
	v_sub_f32_e32 v12, v54, v142
	v_sub_f32_e32 v6, v77, v143
	v_sub_f32_e32 v3, v57, v144
	v_sub_f32_e32 v0, v14, v145
	v_sub_f32_e32 v62, v68, v146
	v_sub_f32_e32 v57, v49, v147
	v_sub_f32_e32 v54, v1, v148
	v_sub_f32_e32 v49, v18, v149
	v_sub_f32_e32 v46, v34, v150
	v_sub_f32_e32 v41, v51, v151
	v_sub_f32_e32 v38, v5, v172
	v_sub_f32_e32 v34, v22, v173
	v_sub_f32_e32 v30, v40, v174
	v_sub_f32_e32 v26, v56, v175
	v_sub_f32_e32 v22, v75, v176
	v_sub_f32_e32 v18, v10, v177
	v_sub_f32_e32 v14, v27, v178
	v_sub_f32_e32 v10, v59, v179
	v_sub_f32_e32 v5, v43, v180
	v_sub_f32_e32 v1, v76, v181
	v_sub_f32_e32 v74, v16, v182
	v_sub_f32_e32 v59, v32, v183
	s_waitcnt lgkmcnt(14)
	v_sub_f32_e32 v56, v48, v184
	v_sub_f32_e32 v51, v2, v185
	s_waitcnt lgkmcnt(13)
	v_sub_f32_e32 v48, v19, v186
	v_sub_f32_e32 v43, v53, v187
	s_waitcnt lgkmcnt(12)
	v_sub_f32_e32 v40, v35, v188
	v_sub_f32_e32 v35, v69, v189
	s_waitcnt lgkmcnt(11)
	v_sub_f32_e32 v32, v7, v190
	v_sub_f32_e32 v27, v24, v191
	s_waitcnt lgkmcnt(10)
	v_sub_f32_e32 v24, v42, v192
	v_sub_f32_e32 v19, v58, v193
	s_waitcnt lgkmcnt(9)
	v_sub_f32_e32 v16, v11, v194
	v_sub_f32_e32 v11, v29, v195
	s_waitcnt lgkmcnt(8)
	v_sub_f32_e32 v7, v45, v196
	v_sub_f32_e32 v2, v61, v197
	s_waitcnt lgkmcnt(7)
	v_sub_f32_e32 v72, v64, v198
	v_sub_f32_e32 v61, v17, v199
	s_waitcnt lgkmcnt(6)
	v_sub_f32_e32 v58, v33, v200
	v_sub_f32_e32 v53, v50, v201
	s_waitcnt lgkmcnt(5)
	v_sub_f32_e32 v50, v4, v202
	v_sub_f32_e32 v45, v21, v203
	s_waitcnt lgkmcnt(4)
	v_sub_f32_e32 v42, v37, v204
	v_sub_f32_e32 v37, v65, v205
	s_waitcnt lgkmcnt(3)
	v_sub_f32_e32 v33, v8, v206
	v_sub_f32_e32 v29, v9, v207
	s_waitcnt lgkmcnt(2)
	v_sub_f32_e32 v25, v25, v208
	v_sub_f32_e32 v21, v66, v209
	s_waitcnt lgkmcnt(0)
	v_sub_f32_e32 v4, v63, v213
	v_sub_f32_e32 v13, v13, v211
	v_sub_f32_e32 v9, v70, v212
	v_sub_f32_e32 v17, v67, v210
	s_waitcnt lgkmcnt(0)
	v_mul_f32_e32 v130, v62, v62
	v_fmac_f32_e32 v130, v60, v60
	v_fmac_f32_e32 v130, v74, v74
	v_fmac_f32_e32 v130, v72, v72
	v_mul_f32_e32 v131, v57, v57
	v_fmac_f32_e32 v131, v55, v55
	v_fmac_f32_e32 v131, v59, v59
	v_fmac_f32_e32 v131, v61, v61
	v_mul_f32_e32 v132, v54, v54
	v_fmac_f32_e32 v132, v52, v52
	v_fmac_f32_e32 v132, v56, v56
	v_fmac_f32_e32 v132, v58, v58
	v_mul_f32_e32 v133, v49, v49
	v_fmac_f32_e32 v133, v47, v47
	v_fmac_f32_e32 v133, v51, v51
	v_fmac_f32_e32 v133, v53, v53
	v_mul_f32_e32 v134, v46, v46
	v_fmac_f32_e32 v134, v44, v44
	v_fmac_f32_e32 v134, v48, v48
	v_fmac_f32_e32 v134, v50, v50
	v_mul_f32_e32 v135, v41, v41
	v_fmac_f32_e32 v135, v39, v39
	v_fmac_f32_e32 v135, v43, v43
	v_fmac_f32_e32 v135, v45, v45
	v_mul_f32_e32 v136, v38, v38
	v_fmac_f32_e32 v136, v36, v36
	v_fmac_f32_e32 v136, v40, v40
	v_fmac_f32_e32 v136, v42, v42
	v_mul_f32_e32 v137, v34, v34
	v_fmac_f32_e32 v137, v31, v31
	v_fmac_f32_e32 v137, v35, v35
	v_fmac_f32_e32 v137, v37, v37
	v_mul_f32_e32 v138, v30, v30
	v_fmac_f32_e32 v138, v28, v28
	v_fmac_f32_e32 v138, v32, v32
	v_fmac_f32_e32 v138, v33, v33
	v_mul_f32_e32 v139, v26, v26
	v_fmac_f32_e32 v139, v23, v23
	v_fmac_f32_e32 v139, v27, v27
	v_fmac_f32_e32 v139, v29, v29
	v_mul_f32_e32 v140, v22, v22
	v_fmac_f32_e32 v140, v20, v20
	v_fmac_f32_e32 v140, v24, v24
	v_fmac_f32_e32 v140, v25, v25
	v_mul_f32_e32 v141, v18, v18
	v_fmac_f32_e32 v141, v15, v15
	v_fmac_f32_e32 v141, v19, v19
	v_fmac_f32_e32 v141, v21, v21
	v_mul_f32_e32 v142, v14, v14
	v_fmac_f32_e32 v142, v12, v12
	v_fmac_f32_e32 v142, v16, v16
	v_fmac_f32_e32 v142, v17, v17
	v_mul_f32_e32 v143, v10, v10
	v_fmac_f32_e32 v143, v6, v6
	v_fmac_f32_e32 v143, v11, v11
	v_fmac_f32_e32 v143, v13, v13
	v_mul_f32_e32 v144, v5, v5
	v_fmac_f32_e32 v144, v3, v3
	v_fmac_f32_e32 v144, v7, v7
	v_fmac_f32_e32 v144, v9, v9
	v_mul_f32_e32 v145, v1, v1
	v_fmac_f32_e32 v145, v0, v0
	v_fmac_f32_e32 v145, v2, v2
	v_fmac_f32_e32 v145, v4, v4
	v_add_f32_dpp v130, v130, v130 quad_perm:[1,0,3,2] row_mask:0xf bank_mask:0xf
	v_add_f32_dpp v131, v131, v131 quad_perm:[1,0,3,2] row_mask:0xf bank_mask:0xf
	v_add_f32_dpp v132, v132, v132 quad_perm:[1,0,3,2] row_mask:0xf bank_mask:0xf
	v_add_f32_dpp v133, v133, v133 quad_perm:[1,0,3,2] row_mask:0xf bank_mask:0xf
	v_add_f32_dpp v134, v134, v134 quad_perm:[1,0,3,2] row_mask:0xf bank_mask:0xf
	v_add_f32_dpp v135, v135, v135 quad_perm:[1,0,3,2] row_mask:0xf bank_mask:0xf
	v_add_f32_dpp v136, v136, v136 quad_perm:[1,0,3,2] row_mask:0xf bank_mask:0xf
	v_add_f32_dpp v137, v137, v137 quad_perm:[1,0,3,2] row_mask:0xf bank_mask:0xf
	v_add_f32_dpp v138, v138, v138 quad_perm:[1,0,3,2] row_mask:0xf bank_mask:0xf
	v_add_f32_dpp v139, v139, v139 quad_perm:[1,0,3,2] row_mask:0xf bank_mask:0xf
	v_add_f32_dpp v140, v140, v140 quad_perm:[1,0,3,2] row_mask:0xf bank_mask:0xf
	v_add_f32_dpp v141, v141, v141 quad_perm:[1,0,3,2] row_mask:0xf bank_mask:0xf
	v_add_f32_dpp v142, v142, v142 quad_perm:[1,0,3,2] row_mask:0xf bank_mask:0xf
	v_add_f32_dpp v143, v143, v143 quad_perm:[1,0,3,2] row_mask:0xf bank_mask:0xf
	v_add_f32_dpp v144, v144, v144 quad_perm:[1,0,3,2] row_mask:0xf bank_mask:0xf
	v_add_f32_dpp v145, v145, v145 quad_perm:[1,0,3,2] row_mask:0xf bank_mask:0xf
	v_add_f32_dpp v130, v130, v130 quad_perm:[2,3,0,1] row_mask:0xf bank_mask:0xf
	v_add_f32_dpp v131, v131, v131 quad_perm:[2,3,0,1] row_mask:0xf bank_mask:0xf
	v_add_f32_dpp v132, v132, v132 quad_perm:[2,3,0,1] row_mask:0xf bank_mask:0xf
	v_add_f32_dpp v133, v133, v133 quad_perm:[2,3,0,1] row_mask:0xf bank_mask:0xf
	v_add_f32_dpp v134, v134, v134 quad_perm:[2,3,0,1] row_mask:0xf bank_mask:0xf
	v_add_f32_dpp v135, v135, v135 quad_perm:[2,3,0,1] row_mask:0xf bank_mask:0xf
	v_add_f32_dpp v136, v136, v136 quad_perm:[2,3,0,1] row_mask:0xf bank_mask:0xf
	v_add_f32_dpp v137, v137, v137 quad_perm:[2,3,0,1] row_mask:0xf bank_mask:0xf
	v_add_f32_dpp v138, v138, v138 quad_perm:[2,3,0,1] row_mask:0xf bank_mask:0xf
	v_add_f32_dpp v139, v139, v139 quad_perm:[2,3,0,1] row_mask:0xf bank_mask:0xf
	v_add_f32_dpp v140, v140, v140 quad_perm:[2,3,0,1] row_mask:0xf bank_mask:0xf
	v_add_f32_dpp v141, v141, v141 quad_perm:[2,3,0,1] row_mask:0xf bank_mask:0xf
	v_add_f32_dpp v142, v142, v142 quad_perm:[2,3,0,1] row_mask:0xf bank_mask:0xf
	v_add_f32_dpp v143, v143, v143 quad_perm:[2,3,0,1] row_mask:0xf bank_mask:0xf
	v_add_f32_dpp v144, v144, v144 quad_perm:[2,3,0,1] row_mask:0xf bank_mask:0xf
	v_add_f32_dpp v145, v145, v145 quad_perm:[2,3,0,1] row_mask:0xf bank_mask:0xf
	v_add_f32_dpp v130, v130, v130 row_half_mirror row_mask:0xf bank_mask:0xf
	v_add_f32_dpp v131, v131, v131 row_half_mirror row_mask:0xf bank_mask:0xf
	v_add_f32_dpp v132, v132, v132 row_half_mirror row_mask:0xf bank_mask:0xf
	v_add_f32_dpp v133, v133, v133 row_half_mirror row_mask:0xf bank_mask:0xf
	v_add_f32_dpp v134, v134, v134 row_half_mirror row_mask:0xf bank_mask:0xf
	v_add_f32_dpp v135, v135, v135 row_half_mirror row_mask:0xf bank_mask:0xf
	v_add_f32_dpp v136, v136, v136 row_half_mirror row_mask:0xf bank_mask:0xf
	v_add_f32_dpp v137, v137, v137 row_half_mirror row_mask:0xf bank_mask:0xf
	v_add_f32_dpp v138, v138, v138 row_half_mirror row_mask:0xf bank_mask:0xf
	v_add_f32_dpp v139, v139, v139 row_half_mirror row_mask:0xf bank_mask:0xf
	v_add_f32_dpp v140, v140, v140 row_half_mirror row_mask:0xf bank_mask:0xf
	v_add_f32_dpp v141, v141, v141 row_half_mirror row_mask:0xf bank_mask:0xf
	v_add_f32_dpp v142, v142, v142 row_half_mirror row_mask:0xf bank_mask:0xf
	v_add_f32_dpp v143, v143, v143 row_half_mirror row_mask:0xf bank_mask:0xf
	v_add_f32_dpp v144, v144, v144 row_half_mirror row_mask:0xf bank_mask:0xf
	v_add_f32_dpp v145, v145, v145 row_half_mirror row_mask:0xf bank_mask:0xf
	v_add_f32_dpp v130, v130, v130 row_mirror row_mask:0xf bank_mask:0xf
	v_add_f32_dpp v131, v131, v131 row_mirror row_mask:0xf bank_mask:0xf
	v_add_f32_dpp v132, v132, v132 row_mirror row_mask:0xf bank_mask:0xf
	v_add_f32_dpp v133, v133, v133 row_mirror row_mask:0xf bank_mask:0xf
	v_add_f32_dpp v134, v134, v134 row_mirror row_mask:0xf bank_mask:0xf
	v_add_f32_dpp v135, v135, v135 row_mirror row_mask:0xf bank_mask:0xf
	v_add_f32_dpp v136, v136, v136 row_mirror row_mask:0xf bank_mask:0xf
	v_add_f32_dpp v137, v137, v137 row_mirror row_mask:0xf bank_mask:0xf
	v_add_f32_dpp v138, v138, v138 row_mirror row_mask:0xf bank_mask:0xf
	v_add_f32_dpp v139, v139, v139 row_mirror row_mask:0xf bank_mask:0xf
	v_add_f32_dpp v140, v140, v140 row_mirror row_mask:0xf bank_mask:0xf
	v_add_f32_dpp v141, v141, v141 row_mirror row_mask:0xf bank_mask:0xf
	v_add_f32_dpp v142, v142, v142 row_mirror row_mask:0xf bank_mask:0xf
	v_add_f32_dpp v143, v143, v143 row_mirror row_mask:0xf bank_mask:0xf
	v_add_f32_dpp v144, v144, v144 row_mirror row_mask:0xf bank_mask:0xf
	v_add_f32_dpp v145, v145, v145 row_mirror row_mask:0xf bank_mask:0xf
	v_mov_b32_e32 v146, v130
	v_mov_b32_e32 v147, v131
	v_mov_b32_e32 v148, v132
	v_mov_b32_e32 v149, v133
	v_mov_b32_e32 v150, v134
	v_mov_b32_e32 v151, v135
	v_mov_b32_e32 v172, v136
	v_mov_b32_e32 v173, v137
	v_mov_b32_e32 v174, v138
	v_mov_b32_e32 v175, v139
	v_mov_b32_e32 v176, v140
	v_mov_b32_e32 v177, v141
	v_mov_b32_e32 v178, v142
	v_mov_b32_e32 v179, v143
	v_mov_b32_e32 v180, v144
	v_mov_b32_e32 v181, v145
	v_permlane16_swap_b32_e32 v130, v146
	v_permlane16_swap_b32_e32 v131, v147
	v_permlane16_swap_b32_e32 v132, v148
	v_permlane16_swap_b32_e32 v133, v149
	v_permlane16_swap_b32_e32 v134, v150
	v_permlane16_swap_b32_e32 v135, v151
	v_permlane16_swap_b32_e32 v136, v172
	v_permlane16_swap_b32_e32 v137, v173
	v_permlane16_swap_b32_e32 v138, v174
	v_permlane16_swap_b32_e32 v139, v175
	v_permlane16_swap_b32_e32 v140, v176
	v_permlane16_swap_b32_e32 v141, v177
	v_permlane16_swap_b32_e32 v142, v178
	v_permlane16_swap_b32_e32 v143, v179
	v_permlane16_swap_b32_e32 v144, v180
	v_permlane16_swap_b32_e32 v145, v181
	v_add_f32_e32 v130, v130, v146
	v_add_f32_e32 v131, v131, v147
	v_add_f32_e32 v132, v132, v148
	v_add_f32_e32 v133, v133, v149
	v_add_f32_e32 v134, v134, v150
	v_add_f32_e32 v135, v135, v151
	v_add_f32_e32 v136, v136, v172
	v_add_f32_e32 v137, v137, v173
	v_add_f32_e32 v138, v138, v174
	v_add_f32_e32 v139, v139, v175
	v_add_f32_e32 v140, v140, v176
	v_add_f32_e32 v141, v141, v177
	v_add_f32_e32 v142, v142, v178
	v_add_f32_e32 v143, v143, v179
	v_add_f32_e32 v144, v144, v180
	v_add_f32_e32 v145, v145, v181
	v_fmamk_f32 v130, v130, 0x3c000000, v153
	v_fmamk_f32 v131, v131, 0x3c000000, v153
	v_fmamk_f32 v132, v132, 0x3c000000, v153
	v_fmamk_f32 v133, v133, 0x3c000000, v153
	v_fmamk_f32 v134, v134, 0x3c000000, v153
	v_fmamk_f32 v135, v135, 0x3c000000, v153
	v_fmamk_f32 v136, v136, 0x3c000000, v153
	v_fmamk_f32 v137, v137, 0x3c000000, v153
	v_fmamk_f32 v138, v138, 0x3c000000, v153
	v_fmamk_f32 v139, v139, 0x3c000000, v153
	v_fmamk_f32 v140, v140, 0x3c000000, v153
	v_fmamk_f32 v141, v141, 0x3c000000, v153
	v_fmamk_f32 v142, v142, 0x3c000000, v153
	v_fmamk_f32 v143, v143, 0x3c000000, v153
	v_fmamk_f32 v144, v144, 0x3c000000, v153
	v_fmamk_f32 v145, v145, 0x3c000000, v153
	v_rsq_f32_e32 v130, v130
	v_rsq_f32_e32 v131, v131
	v_rsq_f32_e32 v132, v132
	v_rsq_f32_e32 v133, v133
	v_rsq_f32_e32 v134, v134
	v_rsq_f32_e32 v135, v135
	v_rsq_f32_e32 v136, v136
	v_rsq_f32_e32 v137, v137
	v_rsq_f32_e32 v138, v138
	v_rsq_f32_e32 v139, v139
	v_rsq_f32_e32 v140, v140
	v_rsq_f32_e32 v141, v141
	v_rsq_f32_e32 v142, v142
	v_rsq_f32_e32 v143, v143
	v_rsq_f32_e32 v144, v144
	v_rsq_f32_e32 v145, v145
	v_lshlrev_b32_e32 v190, 1, v171
	v_mul_u32_u24_e32 v191, 0x440, v170
	v_add3_u32 v190, s34, v190, v191
	v_mul_f32_e32 v182, v60, v130
	v_mul_f32_e32 v183, v62, v130
	v_cvt_pk_bf16_f32 v182, v182, v183
	ds_write_b16 v190, v182
	ds_write_b16_d16_hi v190, v182 offset:64
	v_mul_f32_e32 v184, v74, v130
	v_mul_f32_e32 v185, v72, v130
	v_cvt_pk_bf16_f32 v184, v184, v185
	ds_write_b16 v190, v184 offset:128
	ds_write_b16_d16_hi v190, v184 offset:192
	v_mul_f32_e32 v182, v55, v131
	v_mul_f32_e32 v183, v57, v131
	v_cvt_pk_bf16_f32 v182, v182, v183
	ds_write_b16 v190, v182 offset:272
	ds_write_b16_d16_hi v190, v182 offset:336
	v_mul_f32_e32 v184, v59, v131
	v_mul_f32_e32 v185, v61, v131
	v_cvt_pk_bf16_f32 v184, v184, v185
	ds_write_b16 v190, v184 offset:400
	ds_write_b16_d16_hi v190, v184 offset:464
	v_mul_f32_e32 v182, v52, v132
	v_mul_f32_e32 v183, v54, v132
	v_cvt_pk_bf16_f32 v182, v182, v183
	ds_write_b16 v190, v182 offset:544
	ds_write_b16_d16_hi v190, v182 offset:608
	v_mul_f32_e32 v184, v56, v132
	v_mul_f32_e32 v185, v58, v132
	v_cvt_pk_bf16_f32 v184, v184, v185
	ds_write_b16 v190, v184 offset:672
	ds_write_b16_d16_hi v190, v184 offset:736
	v_mul_f32_e32 v182, v47, v133
	v_mul_f32_e32 v183, v49, v133
	v_cvt_pk_bf16_f32 v182, v182, v183
	ds_write_b16 v190, v182 offset:816
	ds_write_b16_d16_hi v190, v182 offset:880
	v_mul_f32_e32 v184, v51, v133
	v_mul_f32_e32 v185, v53, v133
	v_cvt_pk_bf16_f32 v184, v184, v185
	ds_write_b16 v190, v184 offset:944
	ds_write_b16_d16_hi v190, v184 offset:1008
	v_mul_f32_e32 v182, v44, v134
	v_mul_f32_e32 v183, v46, v134
	v_cvt_pk_bf16_f32 v182, v182, v183
	ds_write_b16 v190, v182 offset:2176
	ds_write_b16_d16_hi v190, v182 offset:2240
	v_mul_f32_e32 v184, v48, v134
	v_mul_f32_e32 v185, v50, v134
	v_cvt_pk_bf16_f32 v184, v184, v185
	ds_write_b16 v190, v184 offset:2304
	ds_write_b16_d16_hi v190, v184 offset:2368
	v_mul_f32_e32 v182, v39, v135
	v_mul_f32_e32 v183, v41, v135
	v_cvt_pk_bf16_f32 v182, v182, v183
	ds_write_b16 v190, v182 offset:2448
	ds_write_b16_d16_hi v190, v182 offset:2512
	v_mul_f32_e32 v184, v43, v135
	v_mul_f32_e32 v185, v45, v135
	v_cvt_pk_bf16_f32 v184, v184, v185
	ds_write_b16 v190, v184 offset:2576
	ds_write_b16_d16_hi v190, v184 offset:2640
	v_mul_f32_e32 v182, v36, v136
	v_mul_f32_e32 v183, v38, v136
	v_cvt_pk_bf16_f32 v182, v182, v183
	ds_write_b16 v190, v182 offset:2720
	ds_write_b16_d16_hi v190, v182 offset:2784
	v_mul_f32_e32 v184, v40, v136
	v_mul_f32_e32 v185, v42, v136
	v_cvt_pk_bf16_f32 v184, v184, v185
	ds_write_b16 v190, v184 offset:2848
	ds_write_b16_d16_hi v190, v184 offset:2912
	v_mul_f32_e32 v182, v31, v137
	v_mul_f32_e32 v183, v34, v137
	v_cvt_pk_bf16_f32 v182, v182, v183
	ds_write_b16 v190, v182 offset:2992
	ds_write_b16_d16_hi v190, v182 offset:3056
	v_mul_f32_e32 v184, v35, v137
	v_mul_f32_e32 v185, v37, v137
	v_cvt_pk_bf16_f32 v184, v184, v185
	ds_write_b16 v190, v184 offset:3120
	ds_write_b16_d16_hi v190, v184 offset:3184
	v_mul_f32_e32 v182, v28, v138
	v_mul_f32_e32 v183, v30, v138
	v_cvt_pk_bf16_f32 v182, v182, v183
	ds_write_b16 v190, v182 offset:4352
	ds_write_b16_d16_hi v190, v182 offset:4416
	v_mul_f32_e32 v184, v32, v138
	v_mul_f32_e32 v185, v33, v138
	v_cvt_pk_bf16_f32 v184, v184, v185
	ds_write_b16 v190, v184 offset:4480
	ds_write_b16_d16_hi v190, v184 offset:4544
	v_mul_f32_e32 v182, v23, v139
	v_mul_f32_e32 v183, v26, v139
	v_cvt_pk_bf16_f32 v182, v182, v183
	ds_write_b16 v190, v182 offset:4624
	ds_write_b16_d16_hi v190, v182 offset:4688
	v_mul_f32_e32 v184, v27, v139
	v_mul_f32_e32 v185, v29, v139
	v_cvt_pk_bf16_f32 v184, v184, v185
	ds_write_b16 v190, v184 offset:4752
	ds_write_b16_d16_hi v190, v184 offset:4816
	v_mul_f32_e32 v182, v20, v140
	v_mul_f32_e32 v183, v22, v140
	v_cvt_pk_bf16_f32 v182, v182, v183
	ds_write_b16 v190, v182 offset:4896
	ds_write_b16_d16_hi v190, v182 offset:4960
	v_mul_f32_e32 v184, v24, v140
	v_mul_f32_e32 v185, v25, v140
	v_cvt_pk_bf16_f32 v184, v184, v185
	ds_write_b16 v190, v184 offset:5024
	ds_write_b16_d16_hi v190, v184 offset:5088
	v_mul_f32_e32 v182, v15, v141
	v_mul_f32_e32 v183, v18, v141
	v_cvt_pk_bf16_f32 v182, v182, v183
	ds_write_b16 v190, v182 offset:5168
	ds_write_b16_d16_hi v190, v182 offset:5232
	v_mul_f32_e32 v184, v19, v141
	v_mul_f32_e32 v185, v21, v141
	v_cvt_pk_bf16_f32 v184, v184, v185
	ds_write_b16 v190, v184 offset:5296
	ds_write_b16_d16_hi v190, v184 offset:5360
	v_mul_f32_e32 v182, v12, v142
	v_mul_f32_e32 v183, v14, v142
	v_cvt_pk_bf16_f32 v182, v182, v183
	ds_write_b16 v190, v182 offset:6528
	ds_write_b16_d16_hi v190, v182 offset:6592
	v_mul_f32_e32 v184, v16, v142
	v_mul_f32_e32 v185, v17, v142
	v_cvt_pk_bf16_f32 v184, v184, v185
	ds_write_b16 v190, v184 offset:6656
	ds_write_b16_d16_hi v190, v184 offset:6720
	v_mul_f32_e32 v182, v6, v143
	v_mul_f32_e32 v183, v10, v143
	v_cvt_pk_bf16_f32 v182, v182, v183
	ds_write_b16 v190, v182 offset:6800
	ds_write_b16_d16_hi v190, v182 offset:6864
	v_mul_f32_e32 v184, v11, v143
	v_mul_f32_e32 v185, v13, v143
	v_cvt_pk_bf16_f32 v184, v184, v185
	ds_write_b16 v190, v184 offset:6928
	ds_write_b16_d16_hi v190, v184 offset:6992
	v_mul_f32_e32 v182, v3, v144
	v_mul_f32_e32 v183, v5, v144
	v_cvt_pk_bf16_f32 v182, v182, v183
	ds_write_b16 v190, v182 offset:7072
	ds_write_b16_d16_hi v190, v182 offset:7136
	v_mul_f32_e32 v184, v7, v144
	v_mul_f32_e32 v185, v9, v144
	v_cvt_pk_bf16_f32 v184, v184, v185
	ds_write_b16 v190, v184 offset:7200
	ds_write_b16_d16_hi v190, v184 offset:7264
	v_mul_f32_e32 v182, v0, v145
	v_mul_f32_e32 v183, v1, v145
	v_cvt_pk_bf16_f32 v182, v182, v183
	ds_write_b16 v190, v182 offset:7344
	ds_write_b16_d16_hi v190, v182 offset:7408
	v_mul_f32_e32 v184, v2, v145
	v_mul_f32_e32 v185, v4, v145
	v_cvt_pk_bf16_f32 v184, v184, v185
	ds_write_b16 v190, v184 offset:7472
	ds_write_b16_d16_hi v190, v184 offset:7536
	s_or_b32 s0, s40, s99
	s_mov_b32 s1, s41
	s_lshl_b64 s[0:1], s[0:1], 11
	v_lshlrev_b32_e32 v0, 1, v169
	v_lshrrev_b32_e32 v6, 4, v168
	v_and_b32_e32 v96, 0xf0, v0
	v_mul_u32_u24_e32 v0, 0x110, v6
	s_add_u32 s0, s92, s0
	v_add3_u32 v8, s34, v96, v0
	s_addc_u32 s1, s93, s1
	s_lshl_b32 s35, s98, 8
	s_add_u32 s0, s0, s35
	s_addc_u32 s1, s1, 0
	s_waitcnt lgkmcnt(0)
	ds_read_b128 v[132:135], v8
	ds_read_b128 v[136:139], v8 offset:1088
	ds_read_b128 v[140:143], v8 offset:2176
	ds_read_b128 v[144:147], v8 offset:3264
	ds_read_b128 v[148:151], v8 offset:4352
	ds_read_b128 v[172:175], v8 offset:5440
	ds_read_b128 v[176:179], v8 offset:6528
	ds_read_b128 v[180:183], v8 offset:7616
	v_lshl_add_u64 v[4:5], s[0:1], 0, v[96:97]
	v_lshlrev_b32_e32 v96, 11, v6
	v_lshl_add_u64 v[6:7], v[4:5], 0, v[96:97]
	s_waitcnt lgkmcnt(7)
	global_store_dwordx4 v[6:7], v[132:135], off sc0 sc1
	v_or_b32_e32 v6, 0x2000, v96
	v_mov_b32_e32 v7, v97
	v_lshl_add_u64 v[6:7], v[4:5], 0, v[6:7]
	s_waitcnt lgkmcnt(6)
	global_store_dwordx4 v[6:7], v[136:139], off sc0 sc1
	v_or_b32_e32 v6, 0x4000, v96
	v_mov_b32_e32 v7, v97
	v_lshl_add_u64 v[6:7], v[4:5], 0, v[6:7]
	s_waitcnt lgkmcnt(5)
	global_store_dwordx4 v[6:7], v[140:143], off sc0 sc1
	v_or_b32_e32 v6, 0x6000, v96
	v_mov_b32_e32 v7, v97
	v_lshl_add_u64 v[6:7], v[4:5], 0, v[6:7]
	s_waitcnt lgkmcnt(4)
	global_store_dwordx4 v[6:7], v[144:147], off sc0 sc1
	v_or_b32_e32 v6, 0x8000, v96
	v_mov_b32_e32 v7, v97
	v_lshl_add_u64 v[6:7], v[4:5], 0, v[6:7]
	s_waitcnt lgkmcnt(3)
	global_store_dwordx4 v[6:7], v[148:151], off sc0 sc1
	v_or_b32_e32 v6, 0xa000, v96
	v_mov_b32_e32 v7, v97
	v_lshl_add_u64 v[6:7], v[4:5], 0, v[6:7]
	s_waitcnt lgkmcnt(2)
	global_store_dwordx4 v[6:7], v[172:175], off sc0 sc1
	v_or_b32_e32 v6, 0xc000, v96
	v_mov_b32_e32 v7, v97
	v_lshl_add_u64 v[6:7], v[4:5], 0, v[6:7]
	s_waitcnt lgkmcnt(1)
	global_store_dwordx4 v[6:7], v[176:179], off sc0 sc1
	v_or_b32_e32 v96, 0xe000, v96
	v_lshl_add_u64 v[4:5], v[4:5], 0, v[96:97]
	s_waitcnt lgkmcnt(0)
	global_store_dwordx4 v[4:5], v[180:183], off sc0 sc1
	s_branch .LBB0_275
